# baseline (speedup 1.0000x reference)
; __device__ __forceinline__ float bf2f(u16 b) { return __uint_as_float(((unsigned)b) << 16); }
; __device__ void final_phase(KP p) {
;   const int tid = tid_v();
;   const int wave = tid >> 6, lane = tid & 63;
;   for (int row = bid_s() * 8 + wave; row < S_; row += gridDim.x * 8) {
;     float ss = (lane < 32) ? p->rowss[(size_t)lane * S_ + row] : 0.f;
;     ss = wave_sum(ss, lane);
;     const float inv = rsqrtf(ss * (1.f / D_) + EPS_);
;     const u16* xr = p->xb + (size_t)row * D_;
;     float* orow = p->xres + (size_t)row * D_;
; #pragma unroll
;     for (int i = 0; i < 4; ++i) {
;       const int c = (lane + 64 * i) * 8;
;       const bf16x8 v = ld_nt16h(xr + c);
;       const float4 g0 = *(const float4*)(p->final_norm + c), g1 = *(const float4*)(p->final_norm + c + 4);
;       float4 o0, o1;
;       o0.x = bf2f((u16)v[0]) * inv * g0.x; o0.y = bf2f((u16)v[1]) * inv * g0.y;
;       o0.z = bf2f((u16)v[2]) * inv * g0.z; o0.w = bf2f((u16)v[3]) * inv * g0.w;
;       o1.x = bf2f((u16)v[4]) * inv * g1.x; o1.y = bf2f((u16)v[5]) * inv * g1.y;
;       o1.z = bf2f((u16)v[6]) * inv * g1.z; o1.w = bf2f((u16)v[7]) * inv * g1.w;
;       st_nt16f(orow + c, o0); st_nt16f(orow + c + 4, o1);
;     }
;   }
; }
.LBB0_10:
	s_cmp_gt_u32 s98, 15
	s_cbranch_scc1 .LBB0_622
	s_cmp_gt_i32 s98, 14
	s_mov_b64 s[4:5], -1
	s_cbranch_scc0 .LBB0_18
	v_mov_b32_e32 v1, v210
	s_mov_b32 s4, s2
	v_ashrrev_i32_e32 v0, 6, v1
	s_nop 0
	v_lshl_add_u32 v0, s4, 3, v0
	v_cmp_gt_i32_e32 vcc, s71, v0
	s_and_saveexec_b64 s[8:9], vcc
	s_cbranch_execz .LBB0_17
	s_load_dwordx4 s[4:7], s[0:1], 0x78
	s_load_dwordx2 s[10:11], s[0:1], 0xb0
	v_and_b32_e32 v1, 63, v1
	v_lshlrev_b32_e32 v12, 3, v1
	v_lshlrev_b32_e32 v2, 2, v1
	v_lshlrev_b32_e32 v192, 5, v1
	v_or_b32_e32 v14, 0x400, v12
	v_xor_b32_e32 v16, 0x80, v2
	s_waitcnt lgkmcnt(0)
	v_lshl_add_u64 v[2:3], s[4:5], 0, v[192:193]
	v_lshlrev_b32_e32 v192, 2, v14
	v_or_b32_e32 v18, 0x600, v12
	v_lshl_add_u64 v[4:5], s[4:5], 0, v[192:193]
	v_lshlrev_b32_e32 v192, 2, v18
	v_lshlrev_b32_e32 v10, 14, v1
	v_lshl_add_u64 v[6:7], s[4:5], 0, v[192:193]
	v_lshlrev_b32_e32 v192, 4, v1
	v_cmp_lt_u32_e32 vcc, 31, v1
	v_lshl_add_u64 v[8:9], s[10:11], 0, v[192:193]
	s_mov_b64 s[10:11], 0
	v_lshlrev_b32_e32 v192, 2, v10
	v_lshlrev_b32_e32 v10, 2, v12
	v_mov_b32_e32 v11, v193
	v_lshlrev_b32_e32 v12, 2, v14
	v_mov_b32_e32 v13, v193
	v_lshlrev_b32_e32 v14, 2, v18
	v_mov_b32_e32 v15, v193
	global_load_dwordx4 v[100:103], v[2:3], off
	global_load_dwordx4 v[104:107], v[2:3], off offset:16
	global_load_dwordx4 v[108:111], v[2:3], off offset:2048
	global_load_dwordx4 v[112:115], v[2:3], off offset:2064
	global_load_dwordx4 v[116:119], v[4:5], off
	global_load_dwordx4 v[120:123], v[4:5], off offset:16
	global_load_dwordx4 v[124:127], v[6:7], off
	global_load_dwordx4 v[128:131], v[6:7], off offset:16
	s_branch .LBB0_15
.LBB0_14:
	s_or_b64 exec, exec, s[4:5]
	v_lshlrev_b64 v[18:19], 12, v[0:1]
	v_lshl_add_u64 v[30:31], v[8:9], 0, v[18:19]
	global_load_dwordx4 v[18:21], v[30:31], off nt
	global_load_dwordx4 v[44:47], v[30:31], off offset:1024 nt
	global_load_dwordx4 v[48:51], v[30:31], off offset:2048 nt
	global_load_dwordx4 v[52:55], v[30:31], off offset:3072 nt
	v_lshlrev_b64 v[32:33], 13, v[0:1]
	v_lshl_add_u64 v[32:33], s[6:7], 0, v[32:33]
	s_waitcnt vmcnt(4)
	ds_swizzle_b32 v60, v17 offset:swizzle(SWAP,1)
	s_waitcnt lgkmcnt(0)
	v_add_f32_e32 v17, v17, v60
	ds_swizzle_b32 v60, v17 offset:swizzle(SWAP,2)
	s_waitcnt lgkmcnt(0)
	v_add_f32_e32 v17, v17, v60
	ds_swizzle_b32 v60, v17 offset:swizzle(SWAP,4)
	s_waitcnt lgkmcnt(0)
	v_add_f32_e32 v17, v17, v60
	ds_swizzle_b32 v60, v17 offset:swizzle(SWAP,8)
	s_waitcnt lgkmcnt(0)
	v_add_f32_e32 v17, v17, v60
	ds_swizzle_b32 v60, v17 offset:swizzle(SWAP,16)
	s_waitcnt lgkmcnt(0)
	v_add_f32_e32 v17, v17, v60
	ds_bpermute_b32 v60, v16, v17
	s_waitcnt lgkmcnt(0)
	v_add_f32_e32 v17, v17, v60
	v_fmamk_f32 v17, v17, 0x3a000000, v211
	v_mul_f32_e32 v60, 0x4b800000, v17
	v_cmp_gt_f32_e64 s[4:5], s77, v17
	v_cndmask_b32_e64 v17, v17, v60, s[4:5]
	v_rsq_f32_e32 v17, v17
	v_lshl_add_u64 v[34:35], v[32:33], 0, v[10:11]
	v_mul_f32_e32 v1, 0x45800000, v17
	v_cndmask_b32_e64 v36, v17, v1, s[4:5]
	v_lshl_add_u64 v[62:63], v[32:33], 0, v[12:13]
	v_lshl_add_u64 v[64:65], v[32:33], 0, v[14:15]
	s_waitcnt vmcnt(3)
	v_lshlrev_b32_e32 v38, 16, v18
	v_and_b32_e32 v39, 0xffff0000, v18
	v_lshlrev_b32_e32 v40, 16, v19
	v_and_b32_e32 v41, 0xffff0000, v19
	v_lshlrev_b32_e32 v66, 16, v20
	v_and_b32_e32 v67, 0xffff0000, v20
	v_lshlrev_b32_e32 v42, 16, v21
	v_and_b32_e32 v43, 0xffff0000, v21
	v_pk_mul_f32 v[38:39], v[36:37], v[38:39] op_sel_hi:[0,1]
	v_pk_mul_f32 v[40:41], v[36:37], v[40:41] op_sel_hi:[0,1]
	v_pk_mul_f32 v[66:67], v[36:37], v[66:67] op_sel_hi:[0,1]
	v_pk_mul_f32 v[42:43], v[36:37], v[42:43] op_sel_hi:[0,1]
	v_pk_mul_f32 v[84:85], v[100:101], v[38:39]
	v_pk_mul_f32 v[86:87], v[102:103], v[40:41]
	v_pk_mul_f32 v[88:89], v[104:105], v[66:67]
	v_pk_mul_f32 v[90:91], v[106:107], v[42:43]
	global_store_dwordx4 v[34:35], v[84:87], off nt
	global_store_dwordx4 v[34:35], v[88:91], off offset:16 nt
	s_waitcnt vmcnt(4)
	v_lshlrev_b32_e32 v38, 16, v44
	v_and_b32_e32 v39, 0xffff0000, v44
	v_lshlrev_b32_e32 v40, 16, v45
	v_and_b32_e32 v41, 0xffff0000, v45
	v_lshlrev_b32_e32 v66, 16, v46
	v_and_b32_e32 v67, 0xffff0000, v46
	v_lshlrev_b32_e32 v42, 16, v47
	v_and_b32_e32 v43, 0xffff0000, v47
	v_pk_mul_f32 v[38:39], v[36:37], v[38:39] op_sel_hi:[0,1]
	v_pk_mul_f32 v[40:41], v[36:37], v[40:41] op_sel_hi:[0,1]
	v_pk_mul_f32 v[66:67], v[36:37], v[66:67] op_sel_hi:[0,1]
	v_pk_mul_f32 v[42:43], v[36:37], v[42:43] op_sel_hi:[0,1]
	v_pk_mul_f32 v[92:93], v[108:109], v[38:39]
	v_pk_mul_f32 v[94:95], v[110:111], v[40:41]
	v_pk_mul_f32 v[96:97], v[112:113], v[66:67]
	v_pk_mul_f32 v[98:99], v[114:115], v[42:43]
	global_store_dwordx4 v[34:35], v[92:95], off offset:2048 nt
	global_store_dwordx4 v[34:35], v[96:99], off offset:2064 nt
	s_waitcnt vmcnt(5)
	v_lshlrev_b32_e32 v38, 16, v48
	v_and_b32_e32 v39, 0xffff0000, v48
	v_lshlrev_b32_e32 v40, 16, v49
	v_and_b32_e32 v41, 0xffff0000, v49
	v_lshlrev_b32_e32 v66, 16, v50
	v_and_b32_e32 v67, 0xffff0000, v50
	v_lshlrev_b32_e32 v42, 16, v51
	v_and_b32_e32 v43, 0xffff0000, v51
	v_pk_mul_f32 v[38:39], v[36:37], v[38:39] op_sel_hi:[0,1]
	v_pk_mul_f32 v[40:41], v[36:37], v[40:41] op_sel_hi:[0,1]
	v_pk_mul_f32 v[66:67], v[36:37], v[66:67] op_sel_hi:[0,1]
	v_pk_mul_f32 v[42:43], v[36:37], v[42:43] op_sel_hi:[0,1]
	v_pk_mul_f32 v[84:85], v[116:117], v[38:39]
	v_pk_mul_f32 v[86:87], v[118:119], v[40:41]
	v_pk_mul_f32 v[88:89], v[120:121], v[66:67]
	v_pk_mul_f32 v[90:91], v[122:123], v[42:43]
	global_store_dwordx4 v[62:63], v[84:87], off nt
	global_store_dwordx4 v[62:63], v[88:91], off offset:16 nt
	s_waitcnt vmcnt(6)
	v_lshlrev_b32_e32 v38, 16, v52
	v_and_b32_e32 v39, 0xffff0000, v52
	v_lshlrev_b32_e32 v40, 16, v53
	v_and_b32_e32 v41, 0xffff0000, v53
	v_lshlrev_b32_e32 v66, 16, v54
	v_and_b32_e32 v67, 0xffff0000, v54
	v_lshlrev_b32_e32 v42, 16, v55
	v_and_b32_e32 v43, 0xffff0000, v55
	v_pk_mul_f32 v[38:39], v[36:37], v[38:39] op_sel_hi:[0,1]
	v_pk_mul_f32 v[40:41], v[36:37], v[40:41] op_sel_hi:[0,1]
	v_pk_mul_f32 v[66:67], v[36:37], v[66:67] op_sel_hi:[0,1]
	v_pk_mul_f32 v[42:43], v[36:37], v[42:43] op_sel_hi:[0,1]
	v_pk_mul_f32 v[92:93], v[124:125], v[38:39]
	v_pk_mul_f32 v[94:95], v[126:127], v[40:41]
	v_pk_mul_f32 v[96:97], v[128:129], v[66:67]
	v_pk_mul_f32 v[98:99], v[130:131], v[42:43]
	global_store_dwordx4 v[64:65], v[92:95], off nt
	global_store_dwordx4 v[64:65], v[96:99], off offset:16 nt
	v_add_u32_e32 v0, s33, v0
	v_cmp_lt_i32_e64 s[4:5], s79, v0
	s_or_b64 s[10:11], s[4:5], s[10:11]
	s_andn2_b64 exec, exec, s[10:11]
	s_cbranch_execz .LBB0_17
